# weight transposer: job-table walk once per wave (lane k = k-th block), later iterations pick fields with v_readlane
# baseline (speedup 1.0000x reference)
; #define JOB(wi_, woff_, ldw_, sc0_, ncols_, K_, doff_, drb_, inter_, gi_, goff_) if (!found) { const int ni = ((K_) / 64) * ((ncols_) / 32); if (r < ni) { wi = (wi_); woff = (size_t)(woff_); ldw = (ldw_); sc0 = (sc0_); nblk = (ncols_) / 32; K = (K_); doff = (size_t)(doff_); drb = (drb_); inter = (inter_); gi = (gi_); goff = (goff_); found = true; } else r -= ni; }
; __device__ __forceinline__ TrJob tr_select(const Params& p, bf16_t* WB, int it) {
;     int r = it; bool found = false;
;     int wi = 0, ldw = 0, sc0 = 0, nblk = 1, K = 64, drb = 0, inter = 0, gi = -1, goff = 0; size_t woff = 0, doff = 0;
;     ...
;     JOB(2, 0, 4096, 0, 4096, 1024, O_A_IN, 0, 0, 1, 0)
;     JOB(7, 0, 1024, 0, 1024, 2048, O_A_OUT, 0, 0, -1, 0)
;     JOB(9, 0, 1024, 0, 1024, 1024, O_B_IN, 0, 0, 8, 0)
;     for (int g = 0; g < 4; ++g) JOB(10, g * 65536, 256, 0, 256, 256, O_B_GRP + g * 65536, 0, 0, -1, 0)
;     JOB(13, 0, 1024, 0, 1024, 1024, O_B_OUT, 0, 0, 12, 0)
;     JOB(15, 0, 2048, 0, 2048, 1024, O_C_IN, 0, 0, 14, 0)
;     for (int h = 0; h < 4; ++h) { JOB(19, h * 65536, 256, 0, 256, 256, O_C_GATE, h * 512, 1, -1, 0) JOB(21, h * 65536, 256, 0, 256, 256, O_C_GATE, h * 512 + 128, 1, -1, 0) }
;     JOB(24, 0, 1024, 0, 1024, 1024, O_C_OUT, 0, 0, -1, 0)
;     JOB(26, 0, 3072, 0, 3072, 1024, O_D_IN, 0, 0, 25, 0)
;     JOB(28, 0, 1024, 0, 1024, 1024, O_D_OUT, 0, 0, -1, 0)
;     for (int l = 0; l < 4; ++l) {
;         JOB(30, (size_t)l * 1024 * 5632, 5632, 0, 2816, 1024, O_F + l * (F_UP_SZ + F_DN_SZ), 0, 1, 29, l * 1024)
;         JOB(30, (size_t)l * 1024 * 5632, 5632, 2816, 2816, 1024, O_F + l * (F_UP_SZ + F_DN_SZ), 128, 1, 29, l * 1024)
;         JOB(33, (size_t)l * 2816 * 1024, 1024, 0, 1024, 2816, O_F + l * (F_UP_SZ + F_DN_SZ) + F_UP_SZ, 0, 0, -1, 0)
;     }
;     ...
;     TrJob j; j.W = p.in[wi] + woff; j.gain = (gi >= 0) ? p.in[gi] + goff : nullptr; j.dst = WB + doff; j.ldw = ldw; j.sc0 = sc0; j.nblk = nblk; j.K = K; j.drb = drb; j.inter = inter; j.r = r; j.found = found;
;     return j;
; }
; __device__ __forceinline__ void prologue_phase(const Params& p, LAS unsigned char* lds, const int tid, const int bx) {
;     ...
;         int it = gw; float cur[32], nxt[32]; TrJob job, jobn;
;         if (it < TOTAL) { job = tr_select(p, WB, it); tr_load(job, cur, lane); }
.LBB0_754:
	s_andn2_b64 vcc, exec, s[4:5]
	v_readlane_b32 s87, v254, 32
	s_movk_i32 s20, 0x7ff
	s_cbranch_vccnz .LBB0_1034
	v_ashrrev_i32_e32 v89, 6, v251
	s_waitcnt vmcnt(0)
	v_mov_b32_e32 v2, v1
	s_waitcnt lgkmcnt(0)
	v_mov_b32_e32 v3, v1
	v_mov_b32_e32 v4, v1
	v_mov_b32_e32 v5, v1
	v_mov_b32_e32 v6, v1
	v_mov_b32_e32 v7, v1
	v_mov_b32_e32 v8, v1
	v_mov_b32_e32 v9, v1
	v_mov_b32_e32 v10, v1
	v_mov_b32_e32 v11, v1
	v_mov_b32_e32 v12, v1
	v_mov_b32_e32 v13, v1
	v_mov_b32_e32 v14, v1
	v_mov_b32_e32 v15, v1
	v_mov_b32_e32 v16, v1
	v_mov_b32_e32 v17, v1
	v_mov_b32_e32 v18, v1
	v_mov_b32_e32 v19, v1
	v_mov_b32_e32 v20, v1
	v_mov_b32_e32 v21, v1
	v_mov_b32_e32 v22, v1
	v_mov_b32_e32 v23, v1
	v_mov_b32_e32 v24, v1
	v_mov_b32_e32 v25, v1
	v_mov_b32_e32 v26, v1
	v_mov_b32_e32 v27, v1
	v_mov_b32_e32 v28, v1
	v_mov_b32_e32 v29, v1
	v_mov_b32_e32 v30, v1
	v_mov_b32_e32 v31, v1
	v_lshl_add_u32 v88, s84, 3, v89
	v_mov_b32_e32 v0, v1
	v_mov_b64_e32 v[32:33], v[30:31]
	v_and_b32_e32 v79, 63, v251
	v_cmp_gt_i32_e32 vcc, s44, v88
	v_mov_b64_e32 v[30:31], v[28:29]
	v_mov_b64_e32 v[28:29], v[26:27]
	v_mov_b64_e32 v[26:27], v[24:25]
	v_mov_b64_e32 v[24:25], v[22:23]
	v_mov_b64_e32 v[22:23], v[20:21]
	v_mov_b64_e32 v[20:21], v[18:19]
	v_mov_b64_e32 v[18:19], v[16:17]
	v_mov_b64_e32 v[16:17], v[14:15]
	v_mov_b64_e32 v[14:15], v[12:13]
	v_mov_b64_e32 v[12:13], v[10:11]
	v_mov_b64_e32 v[10:11], v[8:9]
	v_mov_b64_e32 v[8:9], v[6:7]
	v_mov_b64_e32 v[6:7], v[4:5]
	v_mov_b64_e32 v[4:5], v[2:3]
	v_mov_b64_e32 v[2:3], v[0:1]
	v_mov_b32_e32 v214, v88
	v_mbcnt_lo_u32_b32 v213, -1, 0
	v_mbcnt_hi_u32_b32 v213, -1, v213
	v_lshl_add_u32 v88, v213, 11, v88
	v_cmp_gt_i32_e32 vcc, s44, v88
	s_and_saveexec_b64 s[0:1], vcc
	s_cbranch_execz .LBB0_885
	v_cmp_lt_i32_e64 s[4:5], s20, v88
	v_mov_b32_e32 v11, 2
	v_mov_b32_e32 v10, 0x1000
	v_mov_b32_e32 v92, 0x80
	v_mov_b32_e32 v91, 0x400
	v_mov_b32_e32 v0, 1
	v_mov_b32_e32 v90, v88
	s_and_saveexec_b64 s[6:7], s[4:5]
	v_add_u32_e32 v90, 0xfffff800, v88
	v_mov_b32_e32 v10, 0
	v_mov_b32_e32 v92, 1
	v_mov_b32_e32 v91, 64
	v_mov_b32_e32 v0, -1
	v_mov_b32_e32 v11, 0
	s_or_b64 exec, exec, s[6:7]
	s_mov_b64 s[6:7], -1
	v_mov_b64_e32 v[2:3], 0
	s_mov_b64 s[10:11], -1
	s_and_saveexec_b64 s[8:9], s[4:5]
	s_cbranch_execz .LBB0_762
	v_cmp_lt_i32_e64 s[4:5], s83, v90
	v_mov_b64_e32 v[2:3], 0x400000
	v_mov_b32_e32 v8, -1
	v_mov_b32_e32 v7, 0x800
	v_mov_b32_e32 v6, 32
	v_mov_b32_e32 v5, 0x400
	v_mov_b32_e32 v4, 7
	s_and_saveexec_b64 s[12:13], s[4:5]
	v_add_u32_e32 v90, 0xfffffc00, v90
	v_mov_b64_e32 v[2:3], 0
	s_xor_b64 s[10:11], exec, -1
	v_mov_b32_e32 v4, v11
	v_mov_b32_e32 v5, v10
	v_mov_b32_e32 v6, v92
	v_mov_b32_e32 v7, v91
	v_mov_b32_e32 v8, v0
	s_or_b64 exec, exec, s[12:13]
	s_orn2_b64 s[10:11], s[10:11], exec
	v_mov_b32_e32 v0, v8
	v_mov_b32_e32 v91, v7
	v_mov_b32_e32 v92, v6
	v_mov_b32_e32 v10, v5
	v_mov_b32_e32 v11, v4

; __device__ __forceinline__ TrJob tr_select(const Params& p, bf16_t* WB, int it) {
;     ...
;     TrJob j; j.W = p.in[wi] + woff; j.gain = (gi >= 0) ? p.in[gi] + goff : nullptr; j.dst = WB + doff; j.ldw = ldw; j.sc0 = sc0; j.nblk = nblk; j.K = K; j.drb = drb; j.inter = inter; j.r = r; j.found = found;
;     return j;
; }
; __device__ __forceinline__ void tr_load(const TrJob& j, float (&wv)[32], int lane) {
;     const int kb = j.r / j.nblk, nb = j.r % j.nblk, k0 = 64 * kb, c0 = 32 * nb;
;     const float* src = j.W + (size_t)(k0 + (lane >> 5)) * j.ldw + j.sc0 + c0 + (lane & 31);
; #pragma unroll
;     for (int i = 0; i < 32; ++i) wv[i] = src[(size_t)(2 * i) * j.ldw];
; }
.LBB0_882:
	s_or_b64 exec, exec, s[6:7]
	v_mov_b32_e32 v200, v2
	v_mov_b32_e32 v201, v4
	v_mov_b32_e32 v202, v0
	v_mov_b32_e32 v203, v10
	v_mov_b32_e32 v204, v11
	v_mov_b32_e32 v205, v12
	v_mov_b32_e32 v206, v13
	v_mov_b32_e32 v207, v90
	v_mov_b32_e32 v208, v91
	v_mov_b32_e32 v209, v92
	v_mov_b32_e32 v210, v93
	v_mov_b32_e32 v211, v94
	s_mov_b64 exec, -1
	s_mov_b64 vcc, -1
	v_mov_b32_e32 v88, v214
	v_readlane_b32 s98, v200, 0
	v_mov_b32_e32 v2, s98
	v_readlane_b32 s98, v201, 0
	v_mov_b32_e32 v4, s98
	v_readlane_b32 s98, v202, 0
	v_mov_b32_e32 v0, s98
	v_readlane_b32 s98, v203, 0
	v_mov_b32_e32 v10, s98
	v_readlane_b32 s98, v204, 0
	v_mov_b32_e32 v11, s98
	v_readlane_b32 s98, v205, 0
	v_mov_b32_e32 v12, s98
	v_readlane_b32 s98, v206, 0
	v_mov_b32_e32 v13, s98
	v_readlane_b32 s98, v207, 0
	v_mov_b32_e32 v90, s98
	v_readlane_b32 s98, v208, 0
	v_mov_b32_e32 v91, s98
	v_readlane_b32 s98, v209, 0
	v_mov_b32_e32 v92, s98
	v_readlane_b32 s98, v210, 0
	v_mov_b32_e32 v93, s98
	v_readlane_b32 s98, v211, 0
	v_mov_b32_e32 v94, s98
	v_lshlrev_b32_e32 v3, 3, v11
	global_load_dwordx2 v[6:7], v3, s[68:69]
	v_cmp_lt_i32_e64 s[4:5], -1, v0
	v_mov_b64_e32 v[74:75], 0
	s_and_saveexec_b64 s[6:7], s[4:5]
	s_cbranch_execz .LBB0_884
	v_lshl_add_u64 v[8:9], v[0:1], 3, s[68:69]
	global_load_dwordx2 v[8:9], v[8:9], off
	v_lshlrev_b32_e32 v0, 2, v13
	s_waitcnt vmcnt(0)
	v_lshl_add_u64 v[74:75], v[8:9], 0, v[0:1]

; #define JOB(wi_, woff_, ldw_, sc0_, ncols_, K_, doff_, drb_, inter_, gi_, goff_) if (!found) { const int ni = ((K_) / 64) * ((ncols_) / 32); if (r < ni) { wi = (wi_); woff = (size_t)(woff_); ldw = (ldw_); sc0 = (sc0_); nblk = (ncols_) / 32; K = (K_); doff = (size_t)(doff_); drb = (drb_); inter = (inter_); gi = (gi_); goff = (goff_); found = true; } else r -= ni; }
; __device__ __forceinline__ TrJob tr_select(const Params& p, bf16_t* WB, int it) {
;     int r = it; bool found = false;
;     int wi = 0, ldw = 0, sc0 = 0, nblk = 1, K = 64, drb = 0, inter = 0, gi = -1, goff = 0; size_t woff = 0, doff = 0;
;     ...
;     JOB(2, 0, 4096, 0, 4096, 1024, O_A_IN, 0, 0, 1, 0)
;     JOB(7, 0, 1024, 0, 1024, 2048, O_A_OUT, 0, 0, -1, 0)
;     JOB(9, 0, 1024, 0, 1024, 1024, O_B_IN, 0, 0, 8, 0)
;     for (int g = 0; g < 4; ++g) JOB(10, g * 65536, 256, 0, 256, 256, O_B_GRP + g * 65536, 0, 0, -1, 0)
;     JOB(13, 0, 1024, 0, 1024, 1024, O_B_OUT, 0, 0, 12, 0)
;     JOB(15, 0, 2048, 0, 2048, 1024, O_C_IN, 0, 0, 14, 0)
;     for (int h = 0; h < 4; ++h) { JOB(19, h * 65536, 256, 0, 256, 256, O_C_GATE, h * 512, 1, -1, 0) JOB(21, h * 65536, 256, 0, 256, 256, O_C_GATE, h * 512 + 128, 1, -1, 0) }
;     JOB(24, 0, 1024, 0, 1024, 1024, O_C_OUT, 0, 0, -1, 0)
;     JOB(26, 0, 3072, 0, 3072, 1024, O_D_IN, 0, 0, 25, 0)
;     JOB(28, 0, 1024, 0, 1024, 1024, O_D_OUT, 0, 0, -1, 0)
;     for (int l = 0; l < 4; ++l) {
;         JOB(30, (size_t)l * 1024 * 5632, 5632, 0, 2816, 1024, O_F + l * (F_UP_SZ + F_DN_SZ), 0, 1, 29, l * 1024)
;         JOB(30, (size_t)l * 1024 * 5632, 5632, 2816, 2816, 1024, O_F + l * (F_UP_SZ + F_DN_SZ), 128, 1, 29, l * 1024)
;         JOB(33, (size_t)l * 2816 * 1024, 1024, 0, 1024, 2816, O_F + l * (F_UP_SZ + F_DN_SZ) + F_UP_SZ, 0, 0, -1, 0)
;     }
;     ...
;     TrJob j; j.W = p.in[wi] + woff; j.gain = (gi >= 0) ? p.in[gi] + goff : nullptr; j.dst = WB + doff; j.ldw = ldw; j.sc0 = sc0; j.nblk = nblk; j.K = K; j.drb = drb; j.inter = inter; j.r = r; j.found = found;
;     return j;
; }
; __device__ __forceinline__ void prologue_phase(const Params& p, LAS unsigned char* lds, const int tid, const int bx) {
;     ...
;         while (it < TOTAL) {
;             const int itn = it + NGW; const bool hn = itn < TOTAL;
;             if (hn) { jobn = tr_select(p, WB, itn); tr_load(jobn, nxt, lane); }
.LBB0_888:
	v_add_u32_e32 v102, s48, v102
	s_movk_i32 s3, 0x617f
	v_cmp_gt_i32_e32 vcc, s44, v102
	v_cmp_lt_i32_e64 s[4:5], s3, v102
	s_and_saveexec_b64 s[10:11], vcc
	s_cbranch_execz .LBB0_1018
	v_sub_u32_e32 v215, v102, v214
	v_lshrrev_b32_e32 v215, 11, v215
	s_nop 0
	v_readfirstlane_b32 s98, v215
	s_nop 3
	v_readlane_b32 s99, v200, s98
	v_mov_b32_e32 v34, s99
	v_readlane_b32 s99, v201, s98
	v_mov_b32_e32 v36, s99
	v_readlane_b32 s99, v202, s98
	v_mov_b32_e32 v0, s99
	v_readlane_b32 s99, v203, s98
	v_mov_b32_e32 v42, s99
	v_readlane_b32 s99, v204, s98
	v_mov_b32_e32 v43, s99
	v_readlane_b32 s99, v205, s98
	v_mov_b32_e32 v44, s99
	v_readlane_b32 s99, v206, s98
	v_mov_b32_e32 v45, s99
	v_readlane_b32 s99, v207, s98
	v_mov_b32_e32 v103, s99
	v_readlane_b32 s99, v208, s98
	v_mov_b32_e32 v104, s99
	v_readlane_b32 s99, v209, s98
	v_mov_b32_e32 v105, s99
	v_readlane_b32 s99, v210, s98
	v_mov_b32_e32 v106, s99
	v_readlane_b32 s99, v211, s98
	v_mov_b32_e32 v107, s99
	v_lshlrev_b32_e32 v35, 3, v43
	global_load_dwordx2 v[38:39], v35, s[68:69]
	v_cmp_lt_i32_e64 s[6:7], -1, v0
	v_mov_b64_e32 v[82:83], 0
	s_and_saveexec_b64 s[12:13], s[6:7]
	s_cbranch_execz .LBB0_1017
	v_lshl_add_u64 v[40:41], v[0:1], 3, s[68:69]
	global_load_dwordx2 v[40:41], v[40:41], off
	v_lshlrev_b32_e32 v0, 2, v45
	s_waitcnt vmcnt(0)
	v_lshl_add_u64 v[82:83], v[40:41], 0, v[0:1]
